# v57 + attention QK^T section rewritten: K fragments streamed through a 9-quad register window read 8 ahead, score quads accumulated in place (rope part C=0 then main part), independent MFMAs interleav
# speedup vs baseline: 1.0099x; 1.0023x over previous
.LBB0_581:
	s_or_b64 exec, exec, s[0:1]
	s_min_u32 s0, s19, 0x60
	v_add_u32_e32 v12, s0, v115
	v_mad_u32_u24 v148, v12, s25, v116
	ds_read_b128 v[192:195], v148
	ds_read_b128 v[196:199], v148 offset:576
	ds_read_b128 v[210:213], v148 offset:64
	ds_read_b128 v[214:217], v148 offset:4608
	ds_read_b128 v[218:221], v148 offset:640
	ds_read_b128 v[224:227], v148 offset:5184
	ds_read_b128 v[228:231], v148 offset:4672
	ds_read_b128 v[232:235], v148 offset:9216
	v_add_u32_e32 v149, s19, v87
	s_waitcnt lgkmcnt(7)
	v_mfma_f32_16x16x32_bf16 v[72:75], v[192:195], v[80:83], 0
	ds_read_b128 v[236:239], v148 offset:5248
	s_waitcnt lgkmcnt(7)
	v_mfma_f32_16x16x32_bf16 v[76:79], v[196:199], v[80:83], 0
	ds_read_b128 v[192:195], v148 offset:9792
	s_waitcnt lgkmcnt(7)
	v_mfma_f32_16x16x32_bf16 v[72:75], v[210:213], v[8:11], v[72:75]
	ds_read_b128 v[196:199], v148 offset:9280
	s_waitcnt lgkmcnt(7)
	v_mfma_f32_16x16x32_bf16 v[64:67], v[214:217], v[80:83], 0
	ds_read_b128 v[210:213], v148 offset:13824
	s_waitcnt lgkmcnt(7)
	v_mfma_f32_16x16x32_bf16 v[76:79], v[218:221], v[8:11], v[76:79]
	ds_read_b128 v[214:217], v148 offset:9856
	s_waitcnt lgkmcnt(7)
	v_mfma_f32_16x16x32_bf16 v[68:71], v[224:227], v[80:83], 0
	ds_read_b128 v[218:221], v148 offset:14400
	s_waitcnt lgkmcnt(7)
	v_mfma_f32_16x16x32_bf16 v[64:67], v[228:231], v[8:11], v[64:67]
	ds_read_b128 v[224:227], v148 offset:13888
	s_waitcnt lgkmcnt(7)
	v_mfma_f32_16x16x32_bf16 v[56:59], v[232:235], v[80:83], 0
	ds_read_b128 v[228:231], v148 offset:18432
	s_waitcnt lgkmcnt(7)
	v_mfma_f32_16x16x32_bf16 v[68:71], v[236:239], v[8:11], v[68:71]
	ds_read_b128 v[232:235], v148 offset:14464
	s_waitcnt lgkmcnt(7)
	v_mfma_f32_16x16x32_bf16 v[60:63], v[192:195], v[80:83], 0
	ds_read_b128 v[236:239], v148 offset:19008
	s_waitcnt lgkmcnt(7)
	v_mfma_f32_16x16x32_bf16 v[56:59], v[196:199], v[8:11], v[56:59]
	ds_read_b128 v[192:195], v148 offset:18496
	s_waitcnt lgkmcnt(7)
	v_mfma_f32_16x16x32_bf16 v[44:47], v[210:213], v[80:83], 0
	ds_read_b128 v[196:199], v148 offset:23040
	s_waitcnt lgkmcnt(7)
	v_mfma_f32_16x16x32_bf16 v[60:63], v[214:217], v[8:11], v[60:63]
	ds_read_b128 v[210:213], v148 offset:19072
	s_waitcnt lgkmcnt(7)
	v_mfma_f32_16x16x32_bf16 v[52:55], v[218:221], v[80:83], 0
	ds_read_b128 v[214:217], v148 offset:23616
	s_waitcnt lgkmcnt(7)
	v_mfma_f32_16x16x32_bf16 v[44:47], v[224:227], v[8:11], v[44:47]
	ds_read_b128 v[218:221], v148 offset:23104
	s_waitcnt lgkmcnt(7)
	v_mfma_f32_16x16x32_bf16 v[40:43], v[228:231], v[80:83], 0
	ds_read_b128 v[224:227], v148 offset:27648
	s_waitcnt lgkmcnt(7)
	v_mfma_f32_16x16x32_bf16 v[52:55], v[232:235], v[8:11], v[52:55]
	ds_read_b128 v[228:231], v148 offset:23680
	s_waitcnt lgkmcnt(7)
	v_mfma_f32_16x16x32_bf16 v[48:51], v[236:239], v[80:83], 0
	ds_read_b128 v[232:235], v148 offset:28224
	s_waitcnt lgkmcnt(7)
	v_mfma_f32_16x16x32_bf16 v[40:43], v[192:195], v[8:11], v[40:43]
	ds_read_b128 v[236:239], v148 offset:27712
	s_waitcnt lgkmcnt(7)
	v_mfma_f32_16x16x32_bf16 v[32:35], v[196:199], v[80:83], 0
	ds_read_b128 v[192:195], v148 offset:32256
	s_waitcnt lgkmcnt(7)
	v_mfma_f32_16x16x32_bf16 v[48:51], v[210:213], v[8:11], v[48:51]
	ds_read_b128 v[196:199], v148 offset:28288
	s_waitcnt lgkmcnt(7)
	v_mfma_f32_16x16x32_bf16 v[36:39], v[214:217], v[80:83], 0
	ds_read_b128 v[210:213], v148 offset:32832
	s_waitcnt lgkmcnt(7)
	v_mfma_f32_16x16x32_bf16 v[32:35], v[218:221], v[8:11], v[32:35]
	ds_read_b128 v[214:217], v148 offset:32320
	s_waitcnt lgkmcnt(7)
	v_mfma_f32_16x16x32_bf16 v[24:27], v[224:227], v[80:83], 0
	ds_read_b128 v[218:221], v148 offset:36864
	s_waitcnt lgkmcnt(7)
	v_mfma_f32_16x16x32_bf16 v[36:39], v[228:231], v[8:11], v[36:39]
	ds_read_b128 v[224:227], v148 offset:32896
	s_waitcnt lgkmcnt(7)
	v_mfma_f32_16x16x32_bf16 v[28:31], v[232:235], v[80:83], 0
	ds_read_b128 v[228:231], v148 offset:37440
	s_waitcnt lgkmcnt(7)
	v_mfma_f32_16x16x32_bf16 v[24:27], v[236:239], v[8:11], v[24:27]
	ds_read_b128 v[232:235], v148 offset:36928
	s_waitcnt lgkmcnt(7)
	v_mfma_f32_16x16x32_bf16 v[16:19], v[192:195], v[80:83], 0
	ds_read_b128 v[236:239], v148 offset:37504
	s_waitcnt lgkmcnt(7)
	v_mfma_f32_16x16x32_bf16 v[28:31], v[196:199], v[8:11], v[28:31]
	s_waitcnt lgkmcnt(6)
	v_mfma_f32_16x16x32_bf16 v[20:23], v[210:213], v[80:83], 0
	s_waitcnt lgkmcnt(5)
	v_mfma_f32_16x16x32_bf16 v[16:19], v[214:217], v[8:11], v[16:19]
	s_waitcnt lgkmcnt(4)
	v_mfma_f32_16x16x32_bf16 v[12:15], v[218:221], v[80:83], 0
	s_waitcnt lgkmcnt(3)
	v_mfma_f32_16x16x32_bf16 v[20:23], v[224:227], v[8:11], v[20:23]
	s_waitcnt lgkmcnt(2)
	v_mfma_f32_16x16x32_bf16 v[80:83], v[228:231], v[80:83], 0
	s_waitcnt lgkmcnt(1)
	v_mfma_f32_16x16x32_bf16 v[12:15], v[232:235], v[8:11], v[12:15]
	s_waitcnt lgkmcnt(0)
	v_mfma_f32_16x16x32_bf16 v[8:11], v[236:239], v[8:11], v[80:83]
	v_mul_f32_e32 v72, 0x3e38aa3b, v72
	v_mul_f32_e32 v73, 0x3e38aa3b, v73
	s_nop 4
	v_add_u32_e32 v80, s0, v84
	v_or_b32_e32 v81, 4, v80
	v_cmp_ge_u32_e32 vcc, v80, v149
	v_cmp_le_i32_e64 s[0:1], s60, v80
	s_and_b64 vcc, vcc, s[0:1]
	v_cmp_ge_u32_e64 s[0:1], v81, v149
	v_cmp_le_i32_e64 s[50:51], s60, v81
	s_and_b64 s[0:1], s[0:1], s[50:51]
	v_cndmask_b32_e32 v81, v208, v72, vcc
	v_mul_f32_e32 v72, 0x3e38aa3b, v76
	v_or_b32_e32 v76, 1, v80
	v_cndmask_b32_e64 v82, v208, v72, s[0:1]
	v_or_b32_e32 v83, 5, v80
	v_cmp_ge_u32_e32 vcc, v76, v149
	v_cmp_le_i32_e64 s[0:1], s60, v76
	s_and_b64 vcc, vcc, s[0:1]
	v_cmp_ge_u32_e64 s[0:1], v83, v149
	v_cmp_le_i32_e64 s[50:51], s60, v83
	s_and_b64 s[0:1], s[0:1], s[50:51]
	v_cndmask_b32_e32 v83, v208, v73, vcc
	v_mul_f32_e32 v73, 0x3e38aa3b, v77
	v_cndmask_b32_e64 v144, v208, v73, s[0:1]
	v_max_f32_e32 v72, v81, v82
	v_max_f32_e32 v73, v83, v144
	v_max3_f32 v72, v143, v72, v73
	v_or_b32_e32 v73, 2, v80
	v_or_b32_e32 v76, 6, v80
	v_cmp_ge_u32_e32 vcc, v73, v149
	v_cmp_le_i32_e64 s[0:1], s60, v73
	s_and_b64 vcc, vcc, s[0:1]
	v_cmp_ge_u32_e64 s[0:1], v76, v149
	v_cmp_le_i32_e64 s[50:51], s60, v76
	v_mul_f32_e32 v73, 0x3e38aa3b, v74
	s_and_b64 s[0:1], s[0:1], s[50:51]
	v_cndmask_b32_e32 v145, v208, v73, vcc
	v_mul_f32_e32 v73, 0x3e38aa3b, v78
	v_or_b32_e32 v74, 3, v80
	v_cndmask_b32_e64 v146, v208, v73, s[0:1]
	v_or_b32_e32 v76, 7, v80
	v_cmp_ge_u32_e32 vcc, v74, v149
	v_cmp_le_i32_e64 s[0:1], s60, v74
	s_and_b64 vcc, vcc, s[0:1]
	v_cmp_ge_u32_e64 s[0:1], v76, v149
	v_cmp_le_i32_e64 s[50:51], s60, v76
	v_mul_f32_e32 v74, 0x3e38aa3b, v75
	s_and_b64 s[0:1], s[0:1], s[50:51]
	v_cndmask_b32_e32 v147, v208, v74, vcc
	v_mul_f32_e32 v74, 0x3e38aa3b, v79
	v_cndmask_b32_e64 v148, v208, v74, s[0:1]
	v_max_f32_e32 v73, v145, v146
	v_max_f32_e32 v74, v147, v148
	v_max3_f32 v151, v72, v73, v74
	s_mov_b64 s[0:1], -1
	s_cmp_gt_i32 s59, 62
	s_cbranch_scc1 .LBB0_584
	s_cmp_eq_u32 s59, 0
	s_cselect_b64 s[0:1], -1, 0
	s_cmp_lg_u32 s59, 0
	s_cbranch_scc0 .LBB0_584
	v_pk_mul_f32 v[74:75], v[64:65], s[30:31] op_sel_hi:[1,0]
	v_pk_mul_f32 v[72:73], v[68:69], s[30:31] op_sel_hi:[1,0]
	v_pk_mul_f32 v[78:79], v[66:67], s[30:31] op_sel_hi:[1,0]
	v_max_f32_e32 v76, v74, v72
	v_max_f32_e32 v77, v75, v73
	v_max3_f32 v150, v151, v76, v77
	v_pk_mul_f32 v[76:77], v[70:71], s[30:31] op_sel_hi:[1,0]
	s_nop 0
	v_max_f32_e32 v152, v78, v76
	v_max_f32_e32 v172, v79, v77
	v_max3_f32 v150, v150, v152, v172
